# off-diagonal path: common (no-rescale, P pending) case falls through to one branch into the P.V block; rescale path out of line
# baseline (speedup 1.0000x reference)
; __device__ __forceinline__ void attn_unit(const Params& P, int li, LAS unsigned char* lds, int b, int h, int qb, float lam, float one_m_li) {
;     ...
;             const LAS unsigned char* kp = cb + mp * 8192 + r32 * 128;
;             bf16x8 kf[8];
; #pragma unroll
;             for (int d0 = 0; d0 < 4; ++d0) { kf[2 * d0] = *(const LAS bf16x8*)(kp + coff[d0]); kf[2 * d0 + 1] = *(const LAS bf16x8*)(kp + 4096 + coff[d0]); }
;             const bool diag = (t == cw);
;             if (diag) { p0 = f32x16{}; p1 = f32x16{}; }
;             else {
;                 const float nc0 = -(sl * ((float)((cw - t) * 64) + qinf) + m), nc1 = fadd_s(nc0, sl32);
;                 float b0[4], b1[4];
;                 b0[0] = nc0; b0[1] = fadd_s(nc0, sl8); b0[2] = fma2_s(sl8, nc0); b0[3] = fadd_s(nc0, sl24);
;                 b1[0] = nc1; b1[1] = fadd_s(nc1, sl8); b1[2] = fma2_s(sl8, nc1); b1[3] = fadd_s(nc1, sl24);
; #pragma unroll
;                 for (int q = 0; q < 4; ++q) {
;                     p0[4 * q] = b0[q]; p0[4 * q + 1] = fadd_s(b0[q], sl); p0[4 * q + 2] = fma2_s(sl, b0[q]); p0[4 * q + 3] = fadd_s(b0[q], sl3);
;                     p1[4 * q] = b1[q]; p1[4 * q + 1] = fadd_s(b1[q], sl); p1[4 * q + 2] = fma2_s(sl, b1[q]); p1[4 * q + 3] = fadd_s(b1[q], sl3);
;                 }
;             }
;             __builtin_amdgcn_sched_barrier(0);
;             __builtin_amdgcn_s_setprio(1);
; #pragma unroll
;             for (int d0 = 0; d0 < 4; ++d0) {
;                 p0 = __builtin_amdgcn_mfma_f32_32x32x16_bf16(kf[2 * d0], qr[d0], p0, 0, 0, 0);
;                 p1 = __builtin_amdgcn_mfma_f32_32x32x16_bf16(kf[2 * d0 + 1], qr[d0], p1, 0, 0, 0);
;             }
;             __builtin_amdgcn_s_setprio(0);
;             if (diag) {
;                 float qf = qinf; asm volatile("" : "+v"(qf));
; #pragma unroll
;                 for (int r = 0; r < 16; ++r) { const float d0 = qf - (float)crow(r, 0);
;                     p0[r] = fmaf(-sl, fabsf(d0), p0[r]); p1[r] = fmaf(-sl, fabsf(d0 - 32.f), p1[r]); }
;             }
;             float mx = max3f(p0[0], p1[0], p0[1]);
; #pragma unroll
;             for (int r = 1; r < 15; ++r) mx = max3f(mx, p1[r], p0[r + 1]);
;             mx = max3f(mx, p1[15], mx);
;             const float mt = xor32_max(mx);
;             bool resc; float ra;
;             if (diag) {
;                 resc = true; ra = ex2(m - mt); m = mt;
.Lattn_offdiag:
	s_lshl_b32 s10, s21, 15
	s_and_b32 s22, s10, 0x18000
	v_add_u32_e32 v112, s22, v227
	v_add_u32_e32 v113, v112, v225
	ds_read_b128 v[76:79], v113
	ds_read_b128 v[68:71], v113 offset:4096
	v_add_u32_e32 v113, v112, v224
	ds_read_b128 v[72:75], v113
	ds_read_b128 v[92:95], v113 offset:4096
	v_add_u32_e32 v113, v112, v223
	v_add_u32_e32 v112, v112, v221
	ds_read_b128 v[64:67], v113
	ds_read_b128 v[84:87], v113 offset:4096
	ds_read_b128 v[88:91], v112
	ds_read_b128 v[80:83], v112 offset:4096
	s_sub_i32 s4, s31, s4
	s_lshl_b32 s4, s4, 6
	v_cvt_f32_i32_e32 v112, s4
	v_add_f32_e32 v112, v220, v112
	v_fma_f32 v112, v197, v112, v232
	v_xor_b32_e32 v96, 0x80000000, v112
	v_add_f32_e32 v112, v96, v201
	v_add_f32_e32 v100, v96, v199
	v_fma_f32 v104, v199, 2.0, v96
	v_add_f32_e32 v108, v96, v200
	v_add_f32_e32 v97, v96, v197
	v_fma_f32 v98, v197, 2.0, v96
	v_add_f32_e32 v99, v96, v198
	v_add_f32_e32 v101, v100, v197
	v_fma_f32 v102, v197, 2.0, v100
	v_add_f32_e32 v103, v100, v198
	v_add_f32_e32 v105, v104, v197
	v_fma_f32 v106, v197, 2.0, v104
	v_add_f32_e32 v107, v104, v198
	v_add_f32_e32 v109, v108, v197
	v_fma_f32 v110, v197, 2.0, v108
	v_add_f32_e32 v111, v108, v198
	s_setprio 1
	s_waitcnt lgkmcnt(0)
	v_mfma_f32_32x32x16_bf16 v[96:111], v[76:79], v[128:131], v[96:111]
	v_add_f32_e32 v116, v112, v199
	v_fma_f32 v120, v199, 2.0, v112
	v_add_f32_e32 v124, v112, v200
	v_add_f32_e32 v113, v112, v197
	v_fma_f32 v114, v197, 2.0, v112
	v_mfma_f32_32x32x16_bf16 v[96:111], v[72:75], v[132:135], v[96:111]
	v_add_f32_e32 v115, v112, v198
	v_add_f32_e32 v117, v116, v197
	v_fma_f32 v118, v197, 2.0, v116
	v_add_f32_e32 v119, v116, v198
	v_add_f32_e32 v121, v120, v197
	v_mfma_f32_32x32x16_bf16 v[96:111], v[64:67], v[136:139], v[96:111]
	v_fma_f32 v122, v197, 2.0, v120
	v_add_f32_e32 v123, v120, v198
	v_add_f32_e32 v125, v124, v197
	v_fma_f32 v126, v197, 2.0, v124
	v_add_f32_e32 v127, v124, v198
	v_mfma_f32_32x32x16_bf16 v[96:111], v[88:91], v[140:143], v[96:111]
	s_nop 0
	v_mfma_f32_32x32x16_bf16 v[112:127], v[68:71], v[128:131], v[112:127]
	v_mfma_f32_32x32x16_bf16 v[112:127], v[92:95], v[132:135], v[112:127]
	v_mfma_f32_32x32x16_bf16 v[112:127], v[84:87], v[136:139], v[112:127]
	v_mfma_f32_32x32x16_bf16 v[112:127], v[80:83], v[140:143], v[112:127]
	s_setprio 0
	s_nop 4
	v_max3_f32 v80, v96, v97, v98
	v_max3_f32 v80, v80, v99, v100
	v_max3_f32 v80, v80, v101, v102
	v_max3_f32 v80, v80, v103, v104
	v_max3_f32 v80, v80, v105, v106
	v_max3_f32 v80, v80, v107, v108
	v_max3_f32 v80, v80, v109, v110
	v_max3_f32 v80, v80, v111, v112
	v_max3_f32 v80, v80, v113, v114
	v_max3_f32 v80, v80, v115, v116
	v_max3_f32 v80, v80, v117, v118
	v_max3_f32 v80, v80, v119, v120
	v_max3_f32 v80, v80, v121, v122
	v_max3_f32 v80, v80, v123, v124
	v_max3_f32 v80, v80, v125, v126
	v_max3_f32 v80, v80, v127, v80
	s_nop 0
	v_mov_b32_e32 v81, v80
	s_nop 1
	v_permlane32_swap_b32_e32 v80, v81
	v_max_f32_e32 v233, v80, v81
	s_mov_b32 s4, 0x41000000
	v_cmp_lt_f32_e32 vcc, s4, v233
	s_mov_b64 s[22:23], 0
	s_cbranch_vccnz .Lattn_od_resc
	v_mov_b32_e32 v192, 1.0
	v_mov_b32_e32 v187, v232
	s_mov_b64 s[42:43], 0
.Lattn_od_join:
	s_and_b64 vcc, exec, s[40:41]
	s_mov_b64 s[22:23], -1
	s_cbranch_vccnz .LBB0_436
	s_branch .LBB0_423
.Lattn_od_resc:
	v_max_f32_e32 v80, v233, v233
	v_max_f32_e32 v164, 0, v80
	v_exp_f32_e64 v192, -v164
	v_sub_f32_e32 v111, v111, v164
	v_sub_f32_e32 v110, v110, v164
	v_sub_f32_e32 v109, v109, v164
	v_sub_f32_e32 v108, v108, v164
	v_sub_f32_e32 v107, v107, v164
	v_sub_f32_e32 v106, v106, v164
	v_sub_f32_e32 v105, v105, v164
	v_sub_f32_e32 v104, v104, v164
	v_sub_f32_e32 v103, v103, v164
	v_sub_f32_e32 v102, v102, v164
	v_sub_f32_e32 v101, v101, v164
	v_sub_f32_e32 v100, v100, v164
	v_sub_f32_e32 v99, v99, v164
	v_sub_f32_e32 v98, v98, v164
	v_sub_f32_e32 v97, v97, v164
	v_sub_f32_e32 v96, v96, v164
	v_sub_f32_e32 v127, v127, v164
	v_sub_f32_e32 v126, v126, v164
	v_sub_f32_e32 v125, v125, v164
	v_sub_f32_e32 v124, v124, v164
	v_sub_f32_e32 v123, v123, v164
	v_sub_f32_e32 v122, v122, v164
	v_sub_f32_e32 v121, v121, v164
	v_sub_f32_e32 v120, v120, v164
	v_sub_f32_e32 v119, v119, v164
	v_sub_f32_e32 v118, v118, v164
	v_sub_f32_e32 v117, v117, v164
	v_sub_f32_e32 v116, v116, v164
	v_sub_f32_e32 v115, v115, v164
	v_sub_f32_e32 v114, v114, v164
	v_sub_f32_e32 v113, v113, v164
	v_sub_f32_e32 v112, v112, v164
	v_add_f32_e32 v187, v232, v164
	s_mov_b64 s[42:43], -1
	s_branch .Lattn_od_join
